# ret_out: balanced causal blocks per wave and tile loads issued together; FFN-up bubble weight conversion loads issued together; on top of LN-stat sharing + NSA batched loops
# speedup vs baseline: 1.0051x; 1.0051x over previous
.LBB0_205:
	s_or_saveexec_b64 s[4:5], s[4:5]
	v_mov_b32_e32 v2, 0
	v_mov_b32_e32 v3, 0
	v_mov_b32_e32 v4, 0
	v_mov_b32_e32 v5, 0
	v_mov_b32_e32 v6, 0
	v_mov_b32_e32 v7, 0
	v_mov_b32_e32 v8, 0
	v_mov_b32_e32 v9, 0
	s_xor_b64 exec, exec, s[4:5]
	s_cbranch_execz .LBB0_207
	s_mul_i32 s12, s10, 0xffa80000
	v_ashrrev_i32_e32 v11, 31, v10
	v_add_u32_e32 v8, s12, v16
	v_lshl_add_u64 v[6:7], v[10:11], 2, s[0:1]
	v_ashrrev_i32_e32 v9, 31, v8
	v_add_u32_e32 v4, 0x16000, v8
	v_lshl_add_u64 v[2:3], v[8:9], 2, v[6:7]
	v_ashrrev_i32_e32 v5, 31, v4
	v_lshl_add_u64 v[10:11], v[4:5], 2, v[6:7]
	global_load_dwordx4 v[128:131], v[2:3], off
	global_load_dwordx4 v[132:135], v[10:11], off
	v_add_u32_e32 v2, 0x2c000, v8
	v_add_u32_e32 v8, 0x42000, v8
	v_ashrrev_i32_e32 v3, 31, v2
	v_ashrrev_i32_e32 v9, 31, v8
	v_lshl_add_u64 v[2:3], v[2:3], 2, v[6:7]
	v_lshl_add_u64 v[6:7], v[8:9], 2, v[6:7]
	global_load_dwordx4 v[2:5], v[2:3], off
	s_nop 0
	global_load_dwordx4 v[6:9], v[6:7], off
	s_waitcnt vmcnt(2)
	ds_write2_b32 v17, v128, v129 offset1:1
	ds_write2_b32 v17, v130, v131 offset0:2 offset1:3
	ds_write2_b32 v18, v132, v133 offset1:1
	ds_write2_b32 v19, v134, v135 offset1:1

.LBB0_214:
	s_or_saveexec_b64 s[4:5], s[4:5]
	s_mulk_i32 s8, 0xf500
	v_mov_b32_e32 v2, 0
	v_mov_b32_e32 v3, 0
	v_mov_b32_e32 v4, 0
	v_mov_b32_e32 v5, 0
	v_mov_b32_e32 v6, 0
	v_mov_b32_e32 v7, 0
	v_mov_b32_e32 v8, 0
	v_mov_b32_e32 v9, 0
	s_xor_b64 exec, exec, s[4:5]
	s_cbranch_execz .LBB0_216
	s_add_i32 s9, s8, s6
	v_add_u32_e32 v8, s9, v12
	v_ashrrev_i32_e32 v11, 31, v10
	v_ashrrev_i32_e32 v9, 31, v8
	v_add_u32_e32 v4, 16, v8
	v_lshl_add_u64 v[6:7], v[10:11], 2, s[0:1]
	v_lshlrev_b64 v[2:3], 12, v[8:9]
	v_ashrrev_i32_e32 v5, 31, v4
	v_lshl_add_u64 v[2:3], v[6:7], 0, v[2:3]
	v_lshlrev_b64 v[4:5], 12, v[4:5]
	v_lshl_add_u64 v[10:11], v[6:7], 0, v[4:5]
	global_load_dwordx4 v[128:131], v[2:3], off
	global_load_dwordx4 v[132:135], v[10:11], off
	v_add_u32_e32 v2, 32, v8
	v_add_u32_e32 v8, 48, v8
	v_ashrrev_i32_e32 v3, 31, v2
	v_ashrrev_i32_e32 v9, 31, v8
	v_lshlrev_b64 v[2:3], 12, v[2:3]
	v_lshlrev_b64 v[8:9], 12, v[8:9]
	v_lshl_add_u64 v[2:3], v[6:7], 0, v[2:3]
	v_lshl_add_u64 v[6:7], v[6:7], 0, v[8:9]
	global_load_dwordx4 v[2:5], v[2:3], off
	s_nop 0
	global_load_dwordx4 v[6:9], v[6:7], off
	s_waitcnt vmcnt(2)
	ds_write2_b32 v17, v128, v129 offset1:1
	ds_write2_b32 v17, v130, v131 offset0:2 offset1:3
	ds_write2_b32 v18, v132, v133 offset1:1
	ds_write2_b32 v19, v134, v135 offset1:1

.LBB0_1083:
	s_and_b32 s10, s6, 3
	v_cvt_f32_ubyte0_e32 v0, s10
	v_sub_f32_e32 v0, 0xc0a00000, v0
	s_mov_b32 s0, 0xc2fc0000
	v_cmp_gt_f32_e32 vcc, s0, v0
	s_lshl_b32 s7, s6, 5
	s_and_b32 s43, s7, 0xffffff80
	v_cndmask_b32_e32 v2, 0, v248, vcc
	v_add_f32_e32 v0, v0, v2
	v_exp_f32_e32 v0, v0
	s_and_b64 s[0:1], vcc, exec
	s_cselect_b32 s0, 0xffffffc0, 0
	v_mov_b32_e32 v7, v194
	v_ldexp_f32 v0, v0, s0
	v_readlane_b32 s44, v251, 54
	v_sub_f32_e32 v19, 1.0, v0
	v_lshrrev_b32_e32 v18, 1, v7
	v_mov_b32_e32 v0, s7
	s_movk_i32 s0, 0x7f
	v_readlane_b32 s50, v251, 60
	v_readlane_b32 s51, v251, 61
	v_bfi_b32 v0, s0, v18, v0
	v_and_b32_e32 v28, 1, v7
	v_mov_b64_e32 v[2:3], s[50:51]
	v_mad_i64_i32 v[4:5], s[0:1], v0, s3, v[2:3]
	s_lshl_b32 s88, s10, 8
	v_lshl_add_u64 v[8:9], v[4:5], 0, s[88:89]
	v_lshlrev_b32_e32 v2, 7, v28
	v_mov_b32_e32 v3, v1
	v_lshl_add_u64 v[16:17], v[8:9], 0, v[2:3]
	global_load_dwordx4 v[8:11], v[16:17], off offset:3120
	global_load_dwordx4 v[12:15], v[16:17], off offset:3104
	global_load_dwordx4 v[20:23], v[16:17], off offset:3088
	global_load_dwordx4 v[24:27], v[16:17], off offset:3072
	v_bfe_u32 v6, v7, 1, 7
	v_lshlrev_b32_e32 v0, 6, v28
	v_mul_u32_u24_e32 v28, 0x2200, v28
	v_lshlrev_b32_e32 v28, 1, v28
	v_lshlrev_b32_e32 v29, 1, v6
	v_add3_u32 v30, s4, v28, v29
	v_add3_u32 v28, s4, v29, v28
	s_lshl_b32 s8, s10, 7
	s_mov_b32 s9, s89
	v_lshl_add_u64 v[4:5], v[4:5], 0, s[8:9]
	v_lshl_add_u64 v[4:5], v[4:5], 0, v[0:1]
	s_ashr_i32 s7, s6, 31
	s_lshl_b32 s11, s10, 6
	s_lshl_b64 s[0:1], s[6:7], 15
	s_add_u32 s0, s24, s0
	s_addc_u32 s1, s25, s1
	v_and_b32_e32 v66, 15, v7
	v_cmp_gt_f32_e32 vcc, s69, v19
	v_mul_u32_u24_e32 v67, 0x90, v66
	v_and_b32_e32 v122, 0x60, v18
	v_mul_u32_u24_e32 v69, 0x110, v66
	v_readfirstlane_b32 s64, v122
	s_lshr_b32 s65, s64, 1
	s_and_b32 s2, s65, 16
	s_and_b32 s66, s65, 0x60
	v_mov_b32_e32 v122, s66
	v_or_b32_e32 v125, v122, v66
	v_readlane_b32 s45, v251, 55
	v_readlane_b32 s46, v251, 56
	v_readlane_b32 s47, v251, 57
	v_readlane_b32 s48, v251, 58
	v_readlane_b32 s49, v251, 59
	v_readlane_b32 s52, v251, 62
	v_readlane_b32 s53, v251, 63
	v_readlane_b32 s54, v252, 0
	v_readlane_b32 s55, v252, 1
	v_readlane_b32 s56, v252, 2
	v_readlane_b32 s57, v252, 3
	v_readlane_b32 s58, v252, 4
	v_readlane_b32 s59, v252, 5
	v_lshlrev_b32_e32 v158, 8, v6
	v_mov_b32_e32 v159, v1
	v_lshl_add_u64 v[156:157], s[0:1], 0, v[158:159]
	v_lshl_add_u64 v[156:157], v[156:157], 0, v[2:3]
	global_load_dwordx4 v[140:143], v[16:17], off offset:3184
	global_load_dwordx4 v[144:147], v[16:17], off offset:3168
	global_load_dwordx4 v[148:151], v[16:17], off offset:3152
	global_load_dwordx4 v[152:155], v[16:17], off offset:3136
	global_load_dwordx4 v[160:163], v[4:5], off offset:2560
	global_load_dwordx4 v[164:167], v[4:5], off offset:2576
	global_load_dwordx4 v[168:171], v[4:5], off offset:2592
	global_load_dwordx4 v[172:175], v[4:5], off offset:2608
	global_load_dwordx4 v[176:179], v[156:157], off offset:48
	global_load_dwordx4 v[180:183], v[156:157], off offset:32
	global_load_dwordx4 v[184:187], v[156:157], off offset:16
	global_load_dwordx4 v[188:191], v[156:157], off
	global_load_dwordx4 v[196:199], v[156:157], off offset:112
	global_load_dwordx4 v[200:203], v[156:157], off offset:96
	global_load_dwordx4 v[204:207], v[156:157], off offset:80
	global_load_dwordx4 v[208:211], v[156:157], off offset:64
	s_waitcnt vmcnt(0)
	ds_write_b16 v30, v24
	ds_write_b16_d16_hi v28, v24 offset:272
	ds_write_b16 v30, v25 offset:544
	ds_write_b16_d16_hi v28, v25 offset:816
	ds_write_b16 v30, v26 offset:1088
	ds_write_b16_d16_hi v28, v26 offset:1360
	ds_write_b16 v30, v27 offset:1632
	ds_write_b16_d16_hi v28, v27 offset:1904
	ds_write_b16 v30, v20 offset:2176
	ds_write_b16_d16_hi v28, v20 offset:2448
	ds_write_b16 v30, v21 offset:2720
	ds_write_b16_d16_hi v28, v21 offset:2992
	ds_write_b16 v30, v22 offset:3264
	ds_write_b16_d16_hi v28, v22 offset:3536
	ds_write_b16 v30, v23 offset:3808
	ds_write_b16_d16_hi v28, v23 offset:4080
	ds_write_b16 v30, v12 offset:4352
	ds_write_b16_d16_hi v28, v12 offset:4624
	ds_write_b16 v30, v13 offset:4896
	ds_write_b16_d16_hi v28, v13 offset:5168
	ds_write_b16 v30, v14 offset:5440
	ds_write_b16_d16_hi v28, v14 offset:5712
	ds_write_b16 v30, v15 offset:5984
	ds_write_b16_d16_hi v28, v15 offset:6256
	ds_write_b16 v30, v8 offset:6528
	ds_write_b16_d16_hi v28, v8 offset:6800
	ds_write_b16 v30, v9 offset:7072
	ds_write_b16_d16_hi v28, v9 offset:7344
	ds_write_b16 v30, v10 offset:7616
	ds_write_b16_d16_hi v28, v10 offset:7888
	ds_write_b16 v30, v11 offset:8160
	ds_write_b16_d16_hi v28, v11 offset:8432
	v_mov_b64_e32 v[8:9], v[140:141]
	v_mov_b64_e32 v[10:11], v[142:143]
	v_mov_b64_e32 v[12:13], v[144:145]
	v_mov_b64_e32 v[14:15], v[146:147]
	v_mov_b64_e32 v[20:21], v[148:149]
	v_mov_b64_e32 v[22:23], v[150:151]
	v_mov_b64_e32 v[24:25], v[152:153]
	v_mov_b64_e32 v[26:27], v[154:155]
	ds_write_b16 v30, v24 offset:8704
	ds_write_b16_d16_hi v28, v24 offset:8976
	ds_write_b16 v30, v25 offset:9248
	ds_write_b16_d16_hi v28, v25 offset:9520
	ds_write_b16 v30, v26 offset:9792
	ds_write_b16_d16_hi v28, v26 offset:10064
	ds_write_b16 v30, v27 offset:10336
	ds_write_b16_d16_hi v28, v27 offset:10608
	ds_write_b16 v30, v20 offset:10880
	ds_write_b16_d16_hi v28, v20 offset:11152
	ds_write_b16 v30, v21 offset:11424
	ds_write_b16_d16_hi v28, v21 offset:11696
	ds_write_b16 v30, v22 offset:11968
	ds_write_b16_d16_hi v28, v22 offset:12240
	ds_write_b16 v30, v23 offset:12512
	ds_write_b16_d16_hi v28, v23 offset:12784
	ds_write_b16 v30, v12 offset:13056
	ds_write_b16_d16_hi v28, v12 offset:13328
	ds_write_b16 v30, v13 offset:13600
	ds_write_b16_d16_hi v28, v13 offset:13872
	ds_write_b16 v30, v14 offset:14144
	ds_write_b16_d16_hi v28, v14 offset:14416
	ds_write_b16 v30, v15 offset:14688
	ds_write_b16_d16_hi v28, v15 offset:14960
	ds_write_b16 v30, v8 offset:15232
	ds_write_b16_d16_hi v28, v8 offset:15504
	ds_write_b16 v30, v9 offset:15776
	ds_write_b16_d16_hi v28, v9 offset:16048
	ds_write_b16 v30, v10 offset:16320
	ds_write_b16_d16_hi v28, v10 offset:16592
	ds_write_b16 v30, v11 offset:16864
	ds_write_b16_d16_hi v28, v11 offset:17136
	v_mul_u32_u24_e32 v8, 0x48, v6
	v_lshlrev_b32_e32 v8, 1, v8
	v_add3_u32 v21, s4, v8, v0
	v_mov_b64_e32 v[8:9], v[160:161]
	v_mov_b64_e32 v[10:11], v[162:163]
	v_lshlrev_b32_e32 v0, 8, v6
	v_bfe_u32 v20, v7, 4, 2
	v_lshlrev_b32_e32 v68, 3, v20
	v_lshlrev_b32_e32 v114, 2, v20
	v_add3_u32 v127, v69, v68, s4
	v_sub_u32_e32 v128, v66, v114
	ds_write_b128 v21, v[8:11] offset:34816
	v_mov_b64_e32 v[8:9], v[164:165]
	v_mov_b64_e32 v[10:11], v[166:167]
	ds_write_b128 v21, v[8:11] offset:34832
	v_mov_b64_e32 v[8:9], v[168:169]
	v_mov_b64_e32 v[10:11], v[170:171]
	ds_write_b128 v21, v[8:11] offset:34848
	v_mov_b64_e32 v[8:9], v[172:173]
	v_mov_b64_e32 v[10:11], v[174:175]
	v_lshl_add_u64 v[4:5], s[0:1], 0, v[0:1]
	v_lshl_add_u64 v[22:23], v[4:5], 0, v[2:3]
	s_and_b64 s[0:1], vcc, exec
	s_cselect_b32 s0, 32, 0
	v_ldexp_f32 v0, v19, s0
	v_log_f32_e32 v0, v0
	s_mov_b32 s0, 0x3f317217
	s_lshl_b32 s7, s10, 9
	ds_write_b128 v21, v[8:11] offset:34864
	v_mov_b64_e32 v[2:3], v[176:177]
	v_mov_b64_e32 v[4:5], v[178:179]
	v_mov_b64_e32 v[6:7], v[180:181]
	v_mov_b64_e32 v[8:9], v[182:183]
	v_mov_b64_e32 v[10:11], v[184:185]
	v_mov_b64_e32 v[12:13], v[186:187]
	v_mov_b64_e32 v[14:15], v[188:189]
	v_mov_b64_e32 v[16:17], v[190:191]
	v_cvt_pk_bf16_f32 v6, v6, v7
	v_cvt_pk_bf16_f32 v7, v8, v9
	v_cvt_pk_bf16_f32 v14, v14, v15
	v_cvt_pk_bf16_f32 v15, v16, v17
	v_cvt_pk_bf16_f32 v16, v10, v11
	v_cvt_pk_bf16_f32 v17, v12, v13
	v_cvt_pk_bf16_f32 v8, v2, v3
	v_cvt_pk_bf16_f32 v9, v4, v5
	ds_write_b128 v21, v[14:17] offset:53248
	ds_write_b128 v21, v[6:9] offset:53264
	v_mov_b64_e32 v[2:3], v[196:197]
	v_mov_b64_e32 v[4:5], v[198:199]
	v_mov_b64_e32 v[6:7], v[200:201]
	v_mov_b64_e32 v[8:9], v[202:203]
	v_mov_b64_e32 v[10:11], v[204:205]
	v_mov_b64_e32 v[12:13], v[206:207]
	v_mov_b64_e32 v[14:15], v[208:209]
	v_mov_b64_e32 v[16:17], v[210:211]
	v_cvt_pk_bf16_f32 v6, v6, v7
	v_cvt_pk_bf16_f32 v7, v8, v9
	v_cvt_pk_bf16_f32 v8, v2, v3
	v_mul_f32_e32 v2, 0x3f317217, v0
	v_fma_f32 v2, v0, s0, -v2
	v_fmac_f32_e32 v2, 0x3377d1cf, v0
	s_mov_b32 s0, 0x7f800000
	v_fmac_f32_e32 v2, 0x3f317217, v0
	v_cmp_lt_f32_e64 s[0:1], |v0|, s0
	v_cvt_pk_bf16_f32 v14, v14, v15
	v_cvt_pk_bf16_f32 v15, v16, v17
	v_cndmask_b32_e64 v0, v0, v2, s[0:1]
	v_cndmask_b32_e32 v2, 0, v231, vcc
	v_cmp_lt_i32_e32 vcc, v237, v235
	v_sub_f32_e32 v115, v0, v2
	v_cvt_pk_bf16_f32 v16, v10, v11
	v_cndmask_b32_e32 v0, v234, v237, vcc
	v_cmp_lt_i32_e32 vcc, v236, v235
	v_lshlrev_b32_e32 v123, 2, v0
	v_cvt_pk_bf16_f32 v17, v12, v13
	v_cndmask_b32_e32 v0, v234, v236, vcc
	v_lshlrev_b32_e32 v124, 2, v0
	v_lshlrev_b32_e32 v0, 4, v20
	v_add3_u32 v46, s4, v0, v67
	v_cvt_pk_bf16_f32 v9, v4, v5
	v_add_u32_e32 v54, 0x900, v46
	v_add_u32_e32 v62, 0x1200, v46
	ds_write_b128 v21, v[14:17] offset:53280
	ds_write_b128 v21, v[6:9] offset:53296
	s_waitcnt lgkmcnt(0)
	s_barrier
	ds_read_b128 v[2:5], v46 offset:53248
	ds_read_b128 v[6:9], v46 offset:53312
	ds_read_b128 v[10:13], v46 offset:55552
	ds_read_b128 v[14:17], v46 offset:55616
	ds_read_b128 v[18:21], v46 offset:57856
	ds_read_b128 v[22:25], v46 offset:57920
	ds_read_b128 v[26:29], v46 offset:60160
	ds_read_b128 v[30:33], v46 offset:60224
	ds_read_b128 v[34:37], v46 offset:62464
	ds_read_b128 v[38:41], v46 offset:62528
	ds_read_b128 v[42:45], v46 offset:64768
	ds_read_b128 v[46:49], v46 offset:64832
	ds_read_b128 v[50:53], v54 offset:64768
	ds_read_b128 v[54:57], v54 offset:64832
	ds_read_b128 v[58:61], v62 offset:64768
	ds_read_b128 v[62:65], v62 offset:64832
	s_add_u32 s0, s5, s7
	s_addc_u32 s1, s20, 0
	s_add_u32 s12, s21, s7
	s_addc_u32 s13, s39, 0
	v_lshl_add_u64 v[116:117], s[0:1], 0, v[0:1]
	v_lshl_add_u64 v[118:119], s[12:13], 0, v[0:1]
	v_add3_u32 v126, v67, v0, s42
	s_mov_b64 s[0:1], -1
	s_lshl_b32 s88, s11, 1
	v_lshlrev_b32_e32 v0, 1, v68
	s_lshl_b32 s12, s8, 1

.LBB0_1494:
	s_or_saveexec_b64 s[4:5], s[4:5]
	v_mov_b32_e32 v2, 0
	v_mov_b32_e32 v3, 0
	v_mov_b32_e32 v4, 0
	v_mov_b32_e32 v5, 0
	v_mov_b32_e32 v6, 0
	v_mov_b32_e32 v7, 0
	v_mov_b32_e32 v8, 0
	v_mov_b32_e32 v9, 0
	s_xor_b64 exec, exec, s[4:5]
	s_cbranch_execz .LBB0_1496
	v_readlane_b32 s12, v253, 9
	v_ashrrev_i32_e32 v11, 31, v10
	v_readlane_b32 s13, v253, 10
	s_nop 1
	v_lshl_add_u64 v[6:7], v[10:11], 2, s[12:13]
	s_mul_i32 s12, s10, 0xffa80000
	v_add_u32_e32 v8, s12, v16
	v_ashrrev_i32_e32 v9, 31, v8
	v_add_u32_e32 v4, 0x16000, v8
	v_lshl_add_u64 v[2:3], v[8:9], 2, v[6:7]
	v_ashrrev_i32_e32 v5, 31, v4
	v_lshl_add_u64 v[10:11], v[4:5], 2, v[6:7]
	global_load_dwordx4 v[128:131], v[2:3], off
	global_load_dwordx4 v[132:135], v[10:11], off
	v_add_u32_e32 v2, 0x2c000, v8
	v_add_u32_e32 v8, 0x42000, v8
	v_ashrrev_i32_e32 v3, 31, v2
	v_ashrrev_i32_e32 v9, 31, v8
	v_lshl_add_u64 v[2:3], v[2:3], 2, v[6:7]
	v_lshl_add_u64 v[6:7], v[8:9], 2, v[6:7]
	global_load_dwordx4 v[2:5], v[2:3], off
	s_nop 0
	global_load_dwordx4 v[6:9], v[6:7], off
	s_waitcnt vmcnt(2)
	ds_write2_b32 v17, v128, v129 offset1:1
	ds_write2_b32 v17, v130, v131 offset0:2 offset1:3
	ds_write2_b32 v18, v132, v133 offset1:1
	ds_write2_b32 v19, v134, v135 offset1:1

.LBB0_1503:
	s_or_saveexec_b64 s[4:5], s[4:5]
	s_mulk_i32 s8, 0xf500
	v_mov_b32_e32 v2, 0
	v_mov_b32_e32 v3, 0
	v_mov_b32_e32 v4, 0
	v_mov_b32_e32 v5, 0
	v_mov_b32_e32 v6, 0
	v_mov_b32_e32 v7, 0
	v_mov_b32_e32 v8, 0
	v_mov_b32_e32 v9, 0
	s_xor_b64 exec, exec, s[4:5]
	s_cbranch_execz .LBB0_1505
	s_add_i32 s9, s8, s6
	v_readlane_b32 s10, v253, 11
	v_add_u32_e32 v8, s9, v12
	v_ashrrev_i32_e32 v11, 31, v10
	v_readlane_b32 s11, v253, 12
	v_ashrrev_i32_e32 v9, 31, v8
	v_add_u32_e32 v4, 16, v8
	v_lshl_add_u64 v[6:7], v[10:11], 2, s[10:11]
	v_lshlrev_b64 v[2:3], 12, v[8:9]
	v_ashrrev_i32_e32 v5, 31, v4
	v_lshl_add_u64 v[2:3], v[6:7], 0, v[2:3]
	v_lshlrev_b64 v[4:5], 12, v[4:5]
	v_lshl_add_u64 v[10:11], v[6:7], 0, v[4:5]
	global_load_dwordx4 v[128:131], v[2:3], off
	global_load_dwordx4 v[132:135], v[10:11], off
	v_add_u32_e32 v2, 32, v8
	v_add_u32_e32 v8, 48, v8
	v_ashrrev_i32_e32 v3, 31, v2
	v_ashrrev_i32_e32 v9, 31, v8
	v_lshlrev_b64 v[2:3], 12, v[2:3]
	v_lshlrev_b64 v[8:9], 12, v[8:9]
	v_lshl_add_u64 v[2:3], v[6:7], 0, v[2:3]
	v_lshl_add_u64 v[6:7], v[6:7], 0, v[8:9]
	global_load_dwordx4 v[2:5], v[2:3], off
	s_nop 0
	global_load_dwordx4 v[6:9], v[6:7], off
	s_waitcnt vmcnt(2)
	ds_write2_b32 v17, v128, v129 offset1:1
	ds_write2_b32 v17, v130, v131 offset0:2 offset1:3
	ds_write2_b32 v18, v132, v133 offset1:1
	ds_write2_b32 v19, v134, v135 offset1:1
